# v72 plus norm-row full load batching, FINAL loop batching and removal of the store wait at the top of the second SHIFT loop
# speedup vs baseline: 1.0058x; 1.0058x over previous
.LBB0_2064:
	s_mov_b32 s0, 0x92492493
	v_mul_hi_i32 v1, v2, s0
	v_add_u32_e32 v1, v1, v2
	v_lshrrev_b32_e32 v3, 31, v1
	v_ashrrev_i32_e32 v1, 6, v1
	v_add_u32_e32 v4, v1, v3
	s_movk_i32 s0, 0xfe40
	v_mad_u64_u32 v[6:7], s[0:1], v4, s0, v[0:1]
	s_mov_b32 s0, 0x1c0000
	s_nop 0
	v_cmp_gt_i32_e32 vcc, s0, v2
	v_ashrrev_i32_e32 v5, 31, v4
	s_movk_i32 s0, 0xfc00
	v_cndmask_b32_e32 v1, v227, v238, vcc
	v_lshlrev_b64 v[8:9], 10, v[4:5]
	s_mov_b32 s1, -1
	v_and_b32_e32 v3, v1, v4
	v_lshl_add_u64 v[10:11], v[8:9], 0, s[0:1]
	s_mov_b64 s[0:1], 0x400
	v_cmp_eq_u32_e32 vcc, 0, v3
	s_nop 0
	v_lshl_add_u64 v[12:13], v[8:9], 0, s[0:1]
	v_cmp_eq_u32_e64 s[0:1], v3, v1
	v_cndmask_b32_e32 v11, v11, v9, vcc
	v_cndmask_b32_e32 v10, v10, v8, vcc
	v_cndmask_b32_e64 v9, v13, v9, s[0:1]
	v_cndmask_b32_e64 v8, v12, v8, s[0:1]
	v_lshlrev_b64 v[12:13], 11, v[4:5]
	v_ashrrev_i32_e32 v7, 31, v6
	v_lshl_add_u64 v[12:13], s[6:7], 0, v[12:13]
	v_lshlrev_b64 v[14:15], 1, v[6:7]
	v_lshl_add_u64 v[10:11], v[10:11], 1, s[6:7]
	v_lshl_add_u64 v[8:9], v[8:9], 1, s[6:7]
	v_lshl_add_u64 v[12:13], v[12:13], 0, v[14:15]
	v_lshl_add_u64 v[10:11], v[10:11], 0, v[14:15]
	v_lshl_add_u64 v[8:9], v[8:9], 0, v[14:15]
	global_load_dwordx2 v[16:17], v[12:13], off
	v_cndmask_b32_e64 v18, 0.5, 0, s[0:1]
	global_load_dwordx2 v[10:11], v[10:11], off offset:896
	s_movk_i32 s10, 0xff90
	global_load_dwordx2 v[8:9], v[8:9], off offset:896
	v_cndmask_b32_e64 v14, 0.5, 0, vcc
	v_mad_u64_u32 v[12:13], s[10:11], v4, s10, v[2:3]
	v_cmp_lt_i32_e32 vcc, 31, v12
	s_waitcnt vmcnt(2)
	v_cvt_f32_f16_e32 v20, v16
	v_cvt_f32_f16_sdwa v21, v16 dst_sel:DWORD dst_unused:UNUSED_PAD src0_sel:WORD_1
	s_waitcnt vmcnt(1)
	v_cvt_f32_f16_e32 v22, v10
	v_cvt_f32_f16_sdwa v23, v10 dst_sel:DWORD dst_unused:UNUSED_PAD src0_sel:WORD_1
	s_waitcnt vmcnt(0)
	v_cvt_f32_f16_e32 v24, v8
	v_cvt_f32_f16_e32 v26, v9
	v_cvt_f32_f16_sdwa v27, v9 dst_sel:DWORD dst_unused:UNUSED_PAD src0_sel:WORD_1
	v_cvt_f32_f16_sdwa v25, v8 dst_sel:DWORD dst_unused:UNUSED_PAD src0_sel:WORD_1
	v_cvt_f32_f16_e32 v8, v11
	v_cvt_f32_f16_sdwa v9, v11 dst_sel:DWORD dst_unused:UNUSED_PAD src0_sel:WORD_1
	v_cvt_f32_f16_e32 v16, v17
	v_cvt_f32_f16_sdwa v17, v17 dst_sel:DWORD dst_unused:UNUSED_PAD src0_sel:WORD_1
	v_pk_mul_f32 v[10:11], v[18:19], v[26:27] op_sel_hi:[0,1]
	v_pk_mul_f32 v[18:19], v[18:19], v[24:25] op_sel_hi:[0,1]
	v_pk_fma_f32 v[18:19], v[14:15], v[22:23], v[18:19] op_sel_hi:[0,1,1]
	v_pk_fma_f32 v[8:9], v[14:15], v[8:9], v[10:11] op_sel_hi:[0,1,1]
	v_pk_add_f32 v[8:9], v[16:17], v[8:9]
	v_pk_add_f32 v[10:11], v[20:21], v[18:19]
	s_and_saveexec_b64 s[0:1], vcc
	s_xor_b64 s[0:1], exec, s[0:1]
	s_cbranch_execz .LBB0_2068
	v_subrev_u32_e32 v1, 64, v12
	v_cmp_gt_u32_e32 vcc, 40, v1
	s_and_saveexec_b64 s[10:11], vcc
	s_cbranch_execz .LBB0_2067
	v_mul_f32_e32 v1, 0xbfb8aa3b, v10
	v_exp_f32_e32 v1, v1
	v_mul_f32_e32 v3, 0xbfb8aa3b, v11
	v_mul_f32_e32 v5, 0xbfb8aa3b, v9
	v_exp_f32_e32 v3, v3
	v_add_f32_e32 v1, 1.0, v1
	v_rcp_f32_e32 v10, v1
	v_mul_f32_e32 v1, 0xbfb8aa3b, v8
	v_exp_f32_e32 v1, v1
	v_exp_f32_e32 v5, v5
	v_add_f32_e32 v3, 1.0, v3
	v_rcp_f32_e32 v11, v3
	v_add_f32_e32 v1, 1.0, v1
	v_rcp_f32_e32 v8, v1
	v_add_f32_e32 v1, 1.0, v5
	v_rcp_f32_e32 v9, v1
